# mixin LDS tile padded 16 B per 64-row block: removes 8-way bank conflicts on the hy-part reads
# baseline (speedup 1.0000x reference)
; __device__ __forceinline__ unsigned pk2(float lo, float hi) { return cvtpk(lo, hi); }
; __device__ __forceinline__ float bf2f(bf16_t b) { return __uint_as_float(((unsigned)b) << 16); }
; __device__ void phase_mixin(const Params& p, unsigned char* smem, int wave) {
;     ...
;     for (int it = blockIdx.x; it < NTOK / 64; it += gridDim.x) {
;         const int g0 = it * 64;
;         const int tt = tid >> 3, sub = tid & 7, g = g0 + tt;
;         u32x4 tv[8], av[8], bv[8], cv[8];
;         { const bf16_t* src = hy + (size_t)tid * NTOK + g0;
; #pragma unroll
;           for (int q = 0; q < 8; ++q) tv[q] = *(const u32x4*)(src + 8 * q); }
;         const int h = sub;
;         const float l0 = lse[((size_t)0 * NTOK + g) * 8 + h], l1 = lse[((size_t)1 * NTOK + g) * 8 + h], l2 = lse[((size_t)2 * NTOK + g) * 8 + h];
;         { const bf16_t* o0 = (const bf16_t*)(p.ws + WS_RA) + (size_t)g * 512 + h * 64;
;           const bf16_t* o1 = (const bf16_t*)(p.ws + WS_RA + ATO_STRIDE_01) + (size_t)g * 512 + h * 64;
;           const bf16_t* o2 = (const bf16_t*)(p.ws + WS_ATO2) + (size_t)g * 512 + h * 64;
; #pragma unroll
;           for (int q = 0; q < 8; ++q) { av[q] = *(const u32x4*)(o0 + 8 * q); bv[q] = *(const u32x4*)(o1 + 8 * q); cv[q] = *(const u32x4*)(o2 + 8 * q); } }
;         __syncthreads();
; #pragma unroll
;         for (int q = 0; q < 8; ++q) { unsigned* dst = (unsigned*)(tl + tid * 66 + 8 * q); dst[0] = tv[q].x; dst[1] = tv[q].y; dst[2] = tv[q].z; dst[3] = tv[q].w; }
;         __syncthreads();
;         { float ss = 0.f;
;           for (int c = sub * 64; c < sub * 64 + 64; ++c) { const float v = bf2f(tl[c * 66 + tt]); ss += v * v; }
;           ss += __shfl_xor(ss, 1); ss += __shfl_xor(ss, 2); ss += __shfl_xor(ss, 4);
;           const float r = rsqrtf(ss * (1.f / 512.f) + EPS);
;           bf16_t* dst = mix + (size_t)g * D + sub * 64;
; #pragma unroll
;           for (int q = 0; q < 8; ++q) { float v[8];
; #pragma unroll
;               for (int j = 0; j < 8; ++j) { const int c = sub * 64 + 8 * q + j; v[j] = bf2f(tl[c * 66 + tt]) * r * p.hy_out_g[c]; }
;               u32x4 w; w.x = pk2(v[0], v[1]); w.y = pk2(v[2], v[3]); w.z = pk2(v[4], v[5]); w.w = pk2(v[6], v[7]);
;               *(u32x4*)(dst + 8 * q) = w; } }
.LBB0_744:
	s_cmp_lt_i32 s72, 7
	s_cselect_b64 s[0:1], -1, 0
	s_and_b64 s[4:5], s[0:1], s[4:5]
	s_andn2_b64 vcc, exec, s[4:5]
	s_cbranch_vccnz .LBB0_748
	s_cmpk_gt_i32 s2, 0x4ff
	s_waitcnt vmcnt(0)
	v_mbcnt_lo_u32_b32 v0, -1, 0
	v_mbcnt_hi_u32_b32 v0, -1, v0
	s_cbranch_scc1 .LBB0_748
	v_readlane_b32 s8, v253, 8
	v_readlane_b32 s10, v253, 10
	v_readlane_b32 s11, v253, 11
	v_or_b32_e32 v1, s70, v0
	s_mov_b32 s3, 0x28000
	v_mov_b64_e32 v[2:3], s[10:11]
	v_mad_i64_i32 v[2:3], s[6:7], v1, s3, v[2:3]
	s_mov_b64 s[6:7], 0x24b00000
	s_nop 0
	v_lshl_add_u64 v[104:105], v[2:3], 0, s[6:7]
	v_mbcnt_lo_u32_b32 v2, -1, 0
	v_mbcnt_hi_u32_b32 v2, -1, v2
	v_and_b32_e32 v5, 64, v2
	v_xor_b32_e32 v3, 1, v2
	v_add_u32_e32 v5, 64, v5
	v_cmp_lt_i32_e32 vcc, v3, v5
	v_and_b32_e32 v0, 7, v0
	s_movk_i32 s3, 0x84
	v_cndmask_b32_e32 v3, v2, v3, vcc
	v_lshlrev_b32_e32 v176, 2, v3
	v_xor_b32_e32 v3, 2, v2
	v_cmp_lt_i32_e32 vcc, v3, v5
	v_readlane_b32 s9, v253, 9
	s_add_u32 s4, s10, 0x2eb00000
	v_cndmask_b32_e32 v3, v2, v3, vcc
	v_lshlrev_b32_e32 v177, 2, v3
	v_xor_b32_e32 v3, 4, v2
	v_cmp_lt_i32_e32 vcc, v3, v5
	v_ashrrev_i32_e32 v121, 3, v1
	v_mov_b32_e32 v107, 0
	v_cndmask_b32_e32 v2, v2, v3, vcc
	v_lshlrev_b32_e32 v178, 2, v2
	v_lshl_or_b32 v2, v0, 6, 2
	v_mov_b32_e32 v3, 0xf78
	v_mad_u32_u24 v6, v2, s3, v3
	v_mov_b32_e32 v3, 0x420
	v_lshlrev_b32_e32 v106, 7, v0
	s_addc_u32 s5, s11, 0
	v_lshl_add_u32 v4, v121, 1, 0
	s_movk_i32 s6, 0x2100
	v_mul_u32_u24_e32 v5, 0x84, v2
	v_mad_u32_u24 v7, v2, s3, v3
	v_lshl_add_u64 v[2:3], s[10:11], 0, v[106:107]
	v_readlane_b32 s8, v253, 44
	v_mad_u32_u24 v179, v0, s6, v4
	s_mov_b64 s[6:7], 0x37b00000
	v_readlane_b32 s9, v253, 45
	v_readlane_b32 s10, v253, 46
	v_readlane_b32 s11, v253, 47
	v_readlane_b32 s12, v253, 48
	v_readlane_b32 s13, v253, 49
	v_lshl_add_u64 v[110:111], v[2:3], 0, s[6:7]
	s_mov_b64 s[6:7], 0x29b00000
	v_readlane_b32 s14, v253, 50
	v_readlane_b32 s15, v253, 51
	s_mov_b64 s[8:9], s[12:13]
	v_mul_lo_u32 v1, v1, s3
	v_lshl_add_u64 v[108:109], s[66:67], 0, v[106:107]
	v_lshl_add_u64 v[112:113], v[2:3], 0, s[6:7]
	v_lshlrev_b32_e32 v106, 8, v0
	s_mov_b64 s[10:11], s[14:15]
	s_mov_b64 s[6:7], 0x1b00000
	v_lshl_add_u64 v[114:115], s[8:9], 0, v[106:107]
	v_lshl_add_u64 v[116:117], s[10:11], 0, v[106:107]
	v_mbcnt_lo_u32_b32 v232, -1, 0
	v_mbcnt_hi_u32_b32 v232, -1, v232
	v_lshlrev_b32_e32 v233, 2, v232
	s_lshr_b32 s24, s70, 6
	s_mul_i32 s24, s24, 0x110
	s_add_i32 s24, s24, 0x11000
	v_add_u32_e32 v234, s24, v233
	s_lshl_b32 s25, s70, 2
	v_add_u32_e32 v233, s25, v233
	global_load_dword v235, v233, s[8:9]
	global_load_dword v236, v233, s[10:11]
	v_lshrrev_b32_e32 v230, 4, v106
	s_mov_b32 s25, 0x11000
	v_add3_u32 v230, v230, v106, s25
	s_waitcnt vmcnt(0)
	ds_write_b32 v234, v235
	ds_write_b32 v234, v236 offset:2176
	s_waitcnt lgkmcnt(0)
	s_barrier
	v_lshl_add_u64 v[118:119], v[2:3], 0, s[6:7]
	s_lshl_b32 s6, s2, 6
	s_lshl_b32 s9, s93, 6
	v_lshlrev_b32_e32 v106, 2, v0
	s_mov_b32 s10, 0x280000
	s_mov_b32 s11, 0x500000
	v_add_u32_e32 v180, 0, v1
	v_add_u32_e32 v181, v4, v5
	v_add_u32_e32 v182, v4, v6
	v_add_u32_e32 v183, v4, v7
	v_lshlrev_b32_e32 v237, 4, v0
	v_add_u32_e32 v179, v179, v237
	v_add_u32_e32 v181, v181, v237
	v_add_u32_e32 v182, v182, v237
	v_add_u32_e32 v183, v183, v237
	s_lshr_b32 s24, s70, 2
	v_add_u32_e32 v180, s24, v180
	s_mov_b32 s8, 0x3b000000
	s_mov_b32 s12, 0x800000
	v_mov_b32_e32 v120, 0x358637bd
	s_mov_b32 s13, s2
	v_readlane_b32 s16, v253, 52
	v_readlane_b32 s17, v253, 53
	v_readlane_b32 s18, v253, 54
	v_readlane_b32 s19, v253, 55
	v_readlane_b32 s20, v253, 56
	v_readlane_b32 s21, v253, 57
	v_readlane_b32 s22, v253, 58
	v_readlane_b32 s23, v253, 59
